# p0a folded tiles, pool-kind items: the 8 serialized load+wait rounds replaced by one batch of 9 loads and a single wait
# baseline (speedup 1.0000x reference)
.Lp0a_pool:
	v_ashrrev_i32_e32 v43, 6, v0
	s_mov_b64 s[14:15], 0x1000
	v_add_u32_e32 v43, s30, v43
	v_lshl_or_b32 v44, v43, 6, v4
	v_ashrrev_i32_e32 v45, 31, v44
	global_load_dword v54, v[12:13], off
	v_lshl_add_u64 v[44:45], v[44:45], 2, s[82:83]
	v_lshl_add_u64 v[56:57], v[44:45], 0, s[14:15]
	v_lshl_add_u64 v[58:59], v[56:57], 0, s[14:15]
	v_lshl_add_u64 v[60:61], v[58:59], 0, s[14:15]
	global_load_dword v46, v[44:45], off
	global_load_dword v47, v[44:45], off offset:2048
	global_load_dword v48, v[56:57], off
	global_load_dword v49, v[56:57], off offset:2048
	global_load_dword v50, v[58:59], off
	global_load_dword v51, v[58:59], off offset:2048
	global_load_dword v52, v[60:61], off
	global_load_dword v53, v[60:61], off offset:2048
	s_waitcnt vmcnt(0)
	v_mul_f32_e32 v46, v46, v54
	v_mul_f32_e32 v47, v47, v54
	v_mul_f32_e32 v48, v48, v54
	v_mul_f32_e32 v49, v49, v54
	v_mul_f32_e32 v50, v50, v54
	v_mul_f32_e32 v51, v51, v54
	v_mul_f32_e32 v52, v52, v54
	v_mul_f32_e32 v53, v53, v54
	ds_write_b32 v3, v46
	ds_write_b32 v3, v47 offset:2048
	ds_write_b32 v3, v48 offset:4096
	ds_write_b32 v3, v49 offset:6144
	ds_write_b32 v3, v50 offset:8192
	ds_write_b32 v3, v51 offset:10240
	ds_write_b32 v3, v52 offset:12288
	ds_write_b32 v3, v53 offset:14336
	s_branch .LBB0_67
